# f21 + one static s_setprio 1 for waves 0-3 around the compiler's background tile loop of the diff attention
# baseline (speedup 1.0000x reference)
; __device__ __forceinline__ void bg_load(const BgConv& B, f32x4 (&v)[4], f32x4& gv, int lane) {
;     const int hh = (B.h < BG_NH) ? B.h : BG_NH - 1;
;     const int r = hh >> 1, half = hh & 1, kb = r / 352, nb = r % 352;
;     const float* p = B.src + (size_t)(64 * kb + 4 * half + 8 * (lane & 7)) * (2 * DFF) + 32 * nb + 4 * (lane >> 3);
; #pragma unroll
;     for (int j = 0; j < 4; ++j) v[j] = __builtin_nontemporal_load((const f32x4*)(p + (size_t)j * (2 * DFF)));
;     gv = *(const f32x4*)(B.gain + 64 * kb + 4 * half + 8 * (lane & 7));
; }
;     template <bool BG = false>
;     __device__ __forceinline__ void run(LAS unsigned char* lds, f32x16 (&O)[NCOMP][NBLK], BgConv* bg = nullptr) const {
;     ...
;         if constexpr (BG) {
;             int n = 0; if (bg->h < BG_NH) { n = (BG_NH - 1 - bg->h) / bg->step + 1; const int fit = (ntiles - 1) / 2; n = (n < fit) ? n : fit; }
;             if (n > 0) { bg_load(*bg, bgv, bgg, lane);
; #pragma unroll 1
;                 for (int g = 0; g < n; ++g, t += 2) { body(t, BoolT<true>{}, BoolT<false>{}); body(t + 1, BoolT<true>{}, BoolT<true>{}); } } }
.LBB0_732:
	s_lshl_b32 s87, s81, 2
	v_bfe_u32 v191, v4, 4, 1
	v_and_b32_e32 v192, 3, v4
	v_or_b32_e32 v193, s86, v171
	v_and_b32_e32 v173, 63, v4
	s_sub_i32 s88, s16, s87
	v_bfe_u32 v187, v4, 2, 2
	s_andn2_b64 vcc, exec, s[36:37]
	v_mul_lo_u32 v184, v175, s56
	v_lshlrev_b32_e32 v180, 3, v176
	v_add_u32_e32 v186, s58, v172
	v_mul_lo_u32 v174, v193, s57
	v_lshlrev_b32_e32 v177, 3, v192
	v_lshlrev_b32_e32 v178, 5, v191
	v_add_u32_e32 v188, s59, v172
	v_add_u32_e32 v189, s60, v172
	v_add_u32_e32 v190, s61, v172
	s_cbranch_vccnz .LBB0_739
	s_min_i32 s16, s80, 0x57ff
	s_ashr_i32 s36, s16, 1
	s_mul_hi_i32 s37, s36, 0x2e8ba2e9
	s_lshr_b32 s85, s37, 31
	s_ashr_i32 s37, s37, 6
	s_add_i32 s37, s37, s85
	s_mul_i32 s85, s37, 0x160
	s_lshl_b32 s16, s16, 2
	s_sub_i32 s85, s36, s85
	s_lshl_b32 s36, s37, 6
	s_and_b32 s16, s16, 4
	v_lshlrev_b32_e32 v2, 3, v173
	v_and_b32_e32 v156, 56, v2
	s_or_b32 s37, s36, s16
	v_or_b32_e32 v2, s37, v156
	v_mov_b64_e32 v[8:9], s[50:51]
	v_mad_i64_i32 v[8:9], s[90:91], v2, s54, v[8:9]
	s_lshl_b32 s90, s85, 5
	v_lshrrev_b32_e32 v2, 1, v4
	s_ashr_i32 s91, s90, 31
	v_and_b32_e32 v158, 28, v2
	v_lshl_add_u64 v[8:9], s[90:91], 2, v[8:9]
	v_lshlrev_b32_e32 v2, 2, v158
	v_lshl_add_u64 v[4:5], v[8:9], 0, v[2:3]
	s_ashr_i32 s37, s36, 31
	v_add_co_u32_e32 v8, vcc, s54, v4
	s_lshl_b64 s[36:37], s[36:37], 2
	s_nop 0
	v_addc_co_u32_e32 v9, vcc, 0, v5, vcc
	s_add_u32 s36, s48, s36
	global_load_dwordx4 v[132:135], v[4:5], off nt
	global_load_dwordx4 v[136:139], v[8:9], off nt
	v_add_co_u32_e32 v8, vcc, s43, v4
	s_addc_u32 s37, s49, s37
	s_lshl_b32 s16, s16, 2
	v_addc_co_u32_e32 v9, vcc, 0, v5, vcc
	s_add_u32 s36, s36, s16
	v_add_co_u32_e32 v4, vcc, s55, v4
	s_addc_u32 s37, s37, 0
	v_lshlrev_b32_e32 v2, 2, v156
	v_addc_co_u32_e32 v5, vcc, 0, v5, vcc
	global_load_dwordx4 v[140:143], v[8:9], off nt
	global_load_dwordx4 v[144:147], v[4:5], off nt
	global_load_dwordx4 v[148:151], v2, s[36:37]
	s_lshl_b32 s85, s84, 6
	s_add_i32 s16, s85, s79
	v_lshl_add_u32 v2, v171, 1, s16
	s_lshl_b32 s16, s79, 6
	v_mul_lo_u32 v4, v175, s56
	s_add_i32 s16, s86, s16
	v_add_u32_e32 v8, 0, v4
	v_or_b32_e32 v4, s16, v171
	s_lshl_b32 s36, s72, 4
	v_mul_lo_u32 v4, v4, s57
	v_lshlrev_b32_e32 v5, 3, v176
	s_lshl_b32 s16, s88, 7
	s_lshl_b32 s90, s80, 2
	s_and_b32 s36, s36, 0x600
	v_add3_u32 v9, s58, v4, v5
	v_or_b32_e32 v4, v5, v187
	s_add_u32 s36, s36, s75
	v_mad_u32_u24 v4, v4, s56, 0
	v_lshlrev_b32_e32 v5, 3, v192
	v_lshlrev_b32_e32 v7, 5, v191
	s_addc_u32 s37, 0, s74
	v_add3_u32 v11, v4, v5, v7
	v_mov_b64_e32 v[4:5], s[36:37]
	v_mad_i64_i32 v[4:5], s[36:37], v175, s44, v[4:5]
	v_mov_b32_e32 v7, v3
	v_mul_i32_i24_e32 v185, 0x110, v2
	v_mad_i32_i24 v2, v2, s45, 0
	v_mul_lo_u32 v10, v193, s57
	v_lshl_add_u64 v[4:5], v[4:5], 0, v[6:7]
	v_mov_b32_e32 v181, 0
	v_lshl_add_u64 v[160:161], s[18:19], 0, v[4:5]
	s_lshl_b32 s87, s89, 1
	v_add_u32_e32 v194, v2, v172
	v_add_u32_e32 v195, v8, v179
	v_add_u32_e32 v196, s85, v9
	v_add_u32_e32 v197, v186, v10
	v_add_u32_e32 v198, s16, v11
	v_add_u32_e32 v199, v188, v10
	v_add_u32_e32 v200, v189, v10
	v_add_u32_e32 v201, v190, v10
	v_mov_b32_e32 v4, 0
	v_mov_b32_e32 v5, v181
	v_mov_b32_e32 v6, v181
	v_mov_b32_e32 v7, v181
	v_mov_b32_e32 v8, v181
	v_mov_b32_e32 v9, v181
	v_mov_b32_e32 v10, v181
	v_mov_b32_e32 v11, v181
	v_mov_b32_e32 v12, v181
	v_mov_b32_e32 v13, v181
	v_mov_b32_e32 v14, v181
	v_mov_b32_e32 v15, v181
	v_mov_b32_e32 v16, v181
	v_mov_b32_e32 v17, v181
	v_mov_b32_e32 v18, v181
	v_mov_b32_e32 v19, v181
	v_mov_b32_e32 v20, 0
	v_mov_b32_e32 v21, v181
	v_mov_b32_e32 v22, v181
	v_mov_b32_e32 v23, v181
	v_mov_b32_e32 v24, v181
	v_mov_b32_e32 v25, v181
	v_mov_b32_e32 v26, v181
	v_mov_b32_e32 v27, v181
	v_mov_b32_e32 v28, v181
	v_mov_b32_e32 v29, v181
	v_mov_b32_e32 v30, v181
	v_mov_b32_e32 v31, v181
	v_mov_b32_e32 v32, v181
	v_mov_b32_e32 v33, v181
	v_mov_b32_e32 v34, v181
	v_mov_b32_e32 v35, v181
	v_mov_b32_e32 v36, 0
	v_mov_b32_e32 v37, v181
	v_mov_b32_e32 v38, v181
	v_mov_b32_e32 v39, v181
	v_mov_b32_e32 v40, v181
	v_mov_b32_e32 v41, v181
	v_mov_b32_e32 v42, v181
	v_mov_b32_e32 v43, v181
	v_mov_b32_e32 v44, v181
	v_mov_b32_e32 v45, v181
	v_mov_b32_e32 v46, v181
	v_mov_b32_e32 v47, v181
	v_mov_b32_e32 v48, v181
	v_mov_b32_e32 v49, v181
	v_mov_b32_e32 v50, v181
	v_mov_b32_e32 v51, v181
	v_mov_b32_e32 v52, 0
	v_mov_b32_e32 v53, v181
	v_mov_b32_e32 v54, v181
	v_mov_b32_e32 v55, v181
	v_mov_b32_e32 v56, v181
	v_mov_b32_e32 v57, v181
	v_mov_b32_e32 v58, v181
	v_mov_b32_e32 v59, v181
	v_mov_b32_e32 v60, v181
	v_mov_b32_e32 v61, v181
	v_mov_b32_e32 v62, v181
	v_mov_b32_e32 v63, v181
	v_mov_b32_e32 v64, v181
	v_mov_b32_e32 v65, v181
	v_mov_b32_e32 v66, v181
	v_mov_b32_e32 v67, v181
	v_readfirstlane_b32 s98, v0
	s_nop 3
	s_cmp_ge_u32 s98, 0x100
	s_cbranch_scc1 .Lbgprio_lo
	s_setprio 1
.Lbgprio_lo:
	s_waitcnt vmcnt(5)
	s_branch .LBB0_735

;     template <bool BG = false>
;     __device__ __forceinline__ void run(LAS unsigned char* lds, f32x16 (&O)[NCOMP][NBLK], BgConv* bg = nullptr) const {
;     ...
;         auto body = [&](const int t, auto moret, auto bgt) {
;             constexpr bool more = decltype(moret)::value, BGI = decltype(bgt)::value;
;             if (more) tile_load(kreg, K + (size_t)(64 * (t + 1)) * ldk, ldk, tid);
;             f32x16 st;
; #pragma unroll
;             for (int i = 0; i < 16; ++i) st[i] = 0.f;
;             if (DH == 128) {
;                 bf16x8 kfa[KS];
; #pragma unroll
;                 for (int s = 0; s < KS; ++s) kfa[s] = *(const LAS bf16x8*)(kbuf + ((32 * kh + r) * NCOMP + compA) * KST + (16 * s + 8 * h) * 2);
;                 asm volatile("" ::: "memory");
;                 tile_store_raw(vreg, vbuf, tid);
; #pragma unroll
;                 for (int s = 0; s < KS; ++s) st = MFMA32(kfa[s], qf[s], st);
;             } else {
;             tile_store_raw(vreg, vbuf, tid);
; #pragma unroll
;             for (int s = 0; s < KS; ++s) { const bf16x8 kf = *(const LAS bf16x8*)(kbuf + ((32 * kh + r) * NCOMP + compA) * KST + (16 * s + 8 * h) * 2); st = MFMA32(kf, qf[s], st);
;                 if ((s & 3) == 3) asm volatile("" ::: "memory"); }
;             }
;             float pe[16];
; #pragma unroll
;             for (int i = 0; i < 16; ++i) { pe[i] = fexp2(st[i] - m2); lsum += pe[i]; }
; #pragma unroll
;             for (int g = 0; g < 4; ++g) { u32x2 w; w.x = pk2(pe[4 * g], pe[4 * g + 1]); w.y = pk2(pe[4 * g + 2], pe[4 * g + 3]);
;                 *(LAS u32x2*)(pbuf + ((compA * NRB + rbA) * 32 + r) * PST + (32 * kh + 8 * g + 4 * h) * 2) = w; }
;             __syncthreads();
;             if (more) tile_load(vreg, V + (size_t)(64 * (t + 1)) * ldv, ldv, tid);
; #pragma unroll
;             for (int s = 0; s < 4; ++s) {
;                 bf16x8 pf[NCOMP];
; #pragma unroll
;                 for (int c = 0; c < NCOMP; ++c) pf[c] = *(const LAS bf16x8*)(pbuf + ((c * NRB + rbB) * 32 + r) * PST + (16 * s + 8 * h) * 2);
; #pragma unroll
;                 for (int b = 0; b < NBLK; ++b) {
;                     const bf16x8 vf = trfrag(vbuf + (16 * s + 8 * h + q4) * VST + (DVW * dvp + 32 * b + 16 * b16 + 4 * p4) * 2, 4 * VST);
; #pragma unroll
;                     for (int c = 0; c < NCOMP; ++c) O[c][b] = MFMA32(pf[c], vf, O[c][b]);
;                 }
.LBB0_740:
	s_setprio 0
	s_waitcnt vmcnt(0)
	v_mov_b64_e32 v[160:161], v[152:153]
	v_mov_b64_e32 v[178:179], v[154:155]
	v_and_b32_e32 v202, 31, v0
	v_bfe_u32 v203, v0, 5, 1
	v_bfe_u32 v204, v0, 6, 1
	v_bfe_u32 v205, v0, 7, 1
	v_bfe_u32 v206, v0, 8, 1
	v_lshrrev_b32_e32 v207, 3, v0
	v_and_b32_e32 v208, 7, v0
	v_lshlrev_b32_e32 v209, 1, v202
	v_lshl_add_u32 v209, v204, 6, v209
	v_add_u32_e32 v209, v209, v205
	v_mul_u32_u24_e32 v209, 0x110, v209
	v_lshl_add_u32 v132, v203, 4, v209
	v_lshl_add_u32 v209, v204, 5, v202
	v_mul_u32_u24_e32 v209, 0x110, v209
	v_lshl_add_u32 v209, v203, 4, v209
	v_mul_u32_u24_e32 v211, 0x4400, v205
	v_add_u32_e32 v156, v209, v211
	v_mul_u32_u24_e32 v209, 0x110, v207
	v_lshl_add_u32 v158, v208, 4, v209
	v_mul_u32_u24_e32 v209, 0x240, v207
	v_lshl_add_u32 v209, v208, 4, v209
	v_add_u32_e32 v174, 0x8800, v209
	v_add_u32_e32 v175, 0xe800, v174
	v_lshl_add_u32 v209, v205, 1, v206
	v_lshl_add_u32 v209, v209, 5, v202
	v_mul_u32_u24_e32 v209, 0x90, v209
	v_lshl_add_u32 v209, v204, 6, v209
	v_lshl_add_u32 v209, v203, 3, v209
	v_add_u32_e32 v176, 0x11800, v209
	v_add_u32_e32 v177, 0xe800, v176
	v_lshl_add_u32 v209, v206, 5, v202
	v_mul_u32_u24_e32 v209, 0x90, v209
	v_lshl_add_u32 v209, v203, 4, v209
	v_add_u32_e32 v180, 0x11800, v209
	v_add_u32_e32 v182, 0xe800, v180
	v_bfe_u32 v210, v0, 2, 2
	v_lshl_add_u32 v210, v203, 3, v210
	v_mul_u32_u24_e32 v210, 0x240, v210
	v_bfe_u32 v211, v0, 6, 2
	v_lshl_add_u32 v210, v211, 7, v210
	v_bfe_u32 v211, v0, 4, 1
	v_lshl_add_u32 v210, v211, 5, v210
	v_and_b32_e32 v211, 3, v0
	v_lshl_add_u32 v210, v211, 3, v210
	v_add_u32_e32 v183, 0x8800, v210
	v_add_u32_e32 v184, 0xe800, v183
	s_add_i32 s16, s87, 1
	s_min_u32 s16, s16, s83
	s_lshl_b32 s16, s16, 6
	v_mad_i64_i32 v[250:251], s[88:89], s16, v166, v[160:161]
	global_load_dwordx4 v[234:237], v[250:251], off
	global_load_dwordx4 v[238:241], v[250:251], off offset:128
	global_load_dwordx4 v[242:245], v[250:251], off offset:256
	global_load_dwordx4 v[246:249], v[250:251], off offset:384
	s_add_i32 s16, s87, 1
	s_min_u32 s16, s16, s83
	s_lshl_b32 s16, s16, 6
	v_mad_i64_i32 v[250:251], s[88:89], s16, v166, v[178:179]
	global_load_dwordx4 v[140:143], v[250:251], off
	global_load_dwordx4 v[144:147], v[250:251], off offset:128
	global_load_dwordx4 v[148:151], v[250:251], off offset:256
	global_load_dwordx4 v[152:155], v[250:251], off offset:384
	s_add_i32 s16, s87, 2
	s_min_u32 s16, s16, s83
	s_lshl_b32 s16, s16, 6
	v_mad_i64_i32 v[250:251], s[88:89], s16, v166, v[160:161]
	global_load_dwordx4 v[186:189], v[250:251], off
	global_load_dwordx4 v[190:193], v[250:251], off offset:128
	global_load_dwordx4 v[194:197], v[250:251], off offset:256
	global_load_dwordx4 v[198:201], v[250:251], off offset:384
	ds_read_b128 v[202:205], v132
	ds_read_b128 v[206:209], v132 offset:32
	ds_read_b128 v[210:213], v132 offset:64
	ds_read_b128 v[214:217], v132 offset:96
	ds_read_b128 v[218:221], v132 offset:128
	ds_read_b128 v[222:225], v132 offset:160
	ds_read_b128 v[226:229], v132 offset:192
	ds_read_b128 v[230:233], v132 offset:224
	ds_write_b128 v174, v[128:131]
	ds_write_b128 v174, v[124:127] offset:128
	ds_write_b128 v174, v[120:123] offset:256
	ds_write_b128 v174, v[116:119] offset:384
	s_waitcnt lgkmcnt(11)
	v_mfma_f32_32x32x16_bf16 v[68:83], v[202:205], v[112:115], 0
	s_waitcnt lgkmcnt(10)
	v_mfma_f32_32x32x16_bf16 v[68:83], v[206:209], v[108:111], v[68:83]
	s_waitcnt lgkmcnt(9)
	v_mfma_f32_32x32x16_bf16 v[68:83], v[210:213], v[104:107], v[68:83]
	s_waitcnt lgkmcnt(8)
	v_mfma_f32_32x32x16_bf16 v[68:83], v[214:217], v[100:103], v[68:83]
	s_waitcnt lgkmcnt(7)
	v_mfma_f32_32x32x16_bf16 v[68:83], v[218:221], v[96:99], v[68:83]
	s_waitcnt lgkmcnt(6)
	v_mfma_f32_32x32x16_bf16 v[68:83], v[222:225], v[92:95], v[68:83]
	s_waitcnt lgkmcnt(5)
	v_mfma_f32_32x32x16_bf16 v[68:83], v[226:229], v[88:91], v[68:83]
	s_waitcnt lgkmcnt(4)
	v_mfma_f32_32x32x16_bf16 v[68:83], v[230:233], v[84:87], v[68:83]
	s_nop 11
	v_sub_f32_e32 v68, v68, v170
	v_sub_f32_e32 v69, v69, v170
	v_sub_f32_e32 v70, v70, v170
	v_sub_f32_e32 v71, v71, v170
	v_sub_f32_e32 v72, v72, v170
	v_sub_f32_e32 v73, v73, v170
	v_sub_f32_e32 v74, v74, v170
	v_sub_f32_e32 v75, v75, v170
	v_sub_f32_e32 v76, v76, v170
	v_sub_f32_e32 v77, v77, v170
	v_sub_f32_e32 v78, v78, v170
	v_sub_f32_e32 v79, v79, v170
	v_sub_f32_e32 v80, v80, v170
	v_sub_f32_e32 v81, v81, v170
	v_sub_f32_e32 v82, v82, v170
	v_sub_f32_e32 v83, v83, v170
	v_exp_f32_e32 v68, v68
	v_exp_f32_e32 v69, v69
	v_exp_f32_e32 v70, v70
	v_exp_f32_e32 v71, v71
	v_exp_f32_e32 v72, v72
	v_exp_f32_e32 v73, v73
	v_exp_f32_e32 v74, v74
	v_exp_f32_e32 v75, v75
	v_exp_f32_e32 v76, v76
	v_exp_f32_e32 v77, v77
	v_exp_f32_e32 v78, v78
	v_exp_f32_e32 v79, v79
	v_exp_f32_e32 v80, v80
	v_exp_f32_e32 v81, v81
	v_exp_f32_e32 v82, v82
	v_exp_f32_e32 v83, v83
	v_cvt_pk_bf16_f32 v132, v68, v69
	v_cvt_pk_bf16_f32 v133, v70, v71
	v_cvt_pk_bf16_f32 v134, v72, v73
	v_cvt_pk_bf16_f32 v135, v74, v75
	v_cvt_pk_bf16_f32 v136, v76, v77
	v_cvt_pk_bf16_f32 v137, v78, v79
	v_cvt_pk_bf16_f32 v138, v80, v81
	v_cvt_pk_bf16_f32 v139, v82, v83
	ds_write2_b64 v176, v[132:133], v[134:135] offset1:2
	ds_write2_b64 v176, v[136:137], v[138:139] offset0:4 offset1:6
	v_add_f32_e32 v181, v181, v68
	v_add_f32_e32 v181, v69, v181
	v_add_f32_e32 v181, v70, v181
	v_add_f32_e32 v181, v71, v181
	v_add_f32_e32 v181, v72, v181
	v_add_f32_e32 v181, v73, v181
	v_add_f32_e32 v181, v74, v181
	v_add_f32_e32 v181, v75, v181
	v_add_f32_e32 v181, v76, v181
	v_add_f32_e32 v181, v77, v181
	v_add_f32_e32 v181, v78, v181
	v_add_f32_e32 v181, v79, v181
	v_add_f32_e32 v181, v80, v181
	v_add_f32_e32 v181, v81, v181
	v_add_f32_e32 v181, v82, v181
	v_add_f32_e32 v181, v83, v181
	s_waitcnt lgkmcnt(0)
	s_barrier
	s_waitcnt vmcnt(8)
	ds_write_b128 v158, v[234:237]
	ds_write_b128 v158, v[238:241] offset:128
	ds_write_b128 v158, v[242:245] offset:17408
	ds_write_b128 v158, v[246:249] offset:17536
	s_add_i32 s16, s87, 2
	s_min_u32 s16, s16, s83
	s_lshl_b32 s16, s16, 6
	v_mad_i64_i32 v[250:251], s[88:89], s16, v166, v[178:179]
	global_load_dwordx4 v[128:131], v[250:251], off
	global_load_dwordx4 v[124:127], v[250:251], off offset:128
	global_load_dwordx4 v[120:123], v[250:251], off offset:256
	global_load_dwordx4 v[116:119], v[250:251], off offset:384
	s_add_i32 s16, s87, 3
	s_min_u32 s16, s16, s83
	s_lshl_b32 s16, s16, 6
	v_mad_i64_i32 v[250:251], s[88:89], s16, v166, v[160:161]
	global_load_dwordx4 v[234:237], v[250:251], off
	global_load_dwordx4 v[238:241], v[250:251], off offset:128
	global_load_dwordx4 v[242:245], v[250:251], off offset:256
	global_load_dwordx4 v[246:249], v[250:251], off offset:384
	s_waitcnt lgkmcnt(0)
	s_barrier
	s_cmp_lt_u32 s87, s83
	s_cbranch_scc0 .Lfa_fin_s1
